# scan: loader waves at priority 3 above the compute waves (priority 2) so the next chunk's loads issue at once
# speedup vs baseline: 1.0103x; 1.0103x over previous
; #define LDS_BARRIER() do { asm volatile("s_waitcnt lgkmcnt(0)" ::: "memory"); __builtin_amdgcn_s_barrier(); asm volatile("" ::: "memory"); } while (0)
; __device__ __forceinline__ void phase_scan(h16* Pdn, const h16* Tg, const h16* qkg, const float* gcg, const float* betag, const float* s2g, unsigned char* ldsb) {
;     ...
;         if (w >= 4) {
;             h16x8 R0[15], R1[15], R2[15];
;             SCAN_LD(0, R0); SCAN_ST(0, R0);
;             SCAN_LD(1, R1); SCAN_LD(2, R2); SCAN_LD(3, R0);
;             LDS_BARRIER();
; #pragma unroll 1
;             for (int n = 0; n < 63; n += 3) {
.LBB0_262:
	s_or_b64 exec, exec, s[8:9]
	s_waitcnt lgkmcnt(0)
	s_barrier
	v_mov_b64_e32 v[196:197], 0x600
	v_lshl_add_u64 v[190:191], v[190:191], 2, v[196:197]
	s_mov_b32 s3, 0
	s_mov_b32 s5, 0
	s_setprio 3
	s_branch .LBB0_265

; #define LDS_BARRIER() do { asm volatile("s_waitcnt lgkmcnt(0)" ::: "memory"); __builtin_amdgcn_s_barrier(); asm volatile("" ::: "memory"); } while (0)
; __device__ __forceinline__ void phase_scan(h16* Pdn, const h16* Tg, const h16* qkg, const float* gcg, const float* betag, const float* s2g, unsigned char* ldsb) {
;     ...
;                 LDS_BARRIER();
;             }
;             LDS_BARRIER();
.LBB0_282:
	s_setprio 0
	s_waitcnt lgkmcnt(0)
	s_barrier
